# plus: DeltaNet raw-tile staging (both calls) loads 8 row pieces into private register quads and defers their LDS writes behind a single wait
# baseline (speedup 1.0000x reference)
.LBB0_170:
	s_or_b64 exec, exec, s[2:3]
	s_nop 0
	v_add_f32_dpp v1, v1, v1 row_shr:1 row_mask:0xf bank_mask:0xf bound_ctrl:1
	v_cmp_lt_i32_e32 vcc, 15, v66
	v_ashrrev_i32_e32 v12, 3, v66
	v_add_f32_dpp v1, v1, v1 row_shr:2 row_mask:0xf bank_mask:0xf bound_ctrl:1
	s_lshl_b32 s38, s29, 5
	s_nop 0
	v_add_f32_dpp v1, v1, v1 row_shr:4 row_mask:0xf bank_mask:0xf bound_ctrl:1
	s_nop 1
	v_add_f32_dpp v1, v1, v1 row_shr:8 row_mask:0xf bank_mask:0xf bound_ctrl:1
	s_nop 0
	v_readlane_b32 s2, v1, 15
	v_readlane_b32 s3, v1, 31
	v_readlane_b32 s12, v1, 47
	v_mov_b32_e32 v2, s2
	v_cndmask_b32_e32 v2, 0, v2, vcc
	v_mov_b32_e32 v3, s3
	v_cmp_lt_i32_e32 vcc, 31, v66
	v_readlane_b32 s2, v253, 30
	s_nop 0
	v_cndmask_b32_e32 v3, 0, v3, vcc
	v_add_f32_e32 v2, v2, v3
	v_mov_b32_e32 v3, s12
	v_cmp_lt_i32_e32 vcc, 47, v66
	v_lshl_add_u32 v7, v66, 2, s2
	v_readlane_b32 s2, v253, 27
	v_cndmask_b32_e32 v3, 0, v3, vcc
	v_add_f32_e32 v2, v2, v3
	v_add_f32_e32 v1, v1, v2
	ds_write2st64_b32 v7, v1, v0 offset0:139 offset1:140
	v_and_b32_e32 v0, 7, v66
	v_lshlrev_b32_e32 v171, 3, v0
	v_lshlrev_b32_e32 v0, 4, v0
	v_readlane_b32 s16, v1, 63
	v_mov_b32_e32 v1, v64
	v_add_u32_e32 v170, s2, v0
	s_movk_i32 s2, 0x43
	v_lshl_add_u64 v[4:5], s[82:83], 0, v[0:1]
	v_cmp_gt_i32_e64 s[40:41], s2, v12
	s_and_saveexec_b64 s[2:3], s[40:41]
	s_cbranch_execz .LBB0_183
	v_add_u32_e32 v6, -3, v12
	v_cmp_gt_i32_e32 vcc, 3, v12
	s_and_saveexec_b64 s[12:13], vcc
	s_xor_b64 s[12:13], exec, s[12:13]
	s_cbranch_execz .LBB0_178
	s_cmp_lt_i32 s18, 0
	s_mov_b64 s[20:21], -1
	s_cbranch_scc0 .LBB0_175
	s_cmp_eq_u32 s17, 0
	s_cbranch_scc1 .LBB0_814
	v_add_u32_e32 v0, s31, v6
	v_mad_i64_i32 v[0:1], s[20:21], v0, s97, v[4:5]
	v_readlane_b32 s20, v252, 0
	v_readlane_b32 s21, v252, 1
	s_nop 1
	v_lshl_add_u64 v[0:1], s[20:21], 1, v[0:1]
	global_load_dwordx4 v[178:181], v[0:1], off
	s_mov_b64 s[20:21], 0

.LBB0_176:
	s_add_i32 s20, s18, s38
	v_ashrrev_i32_e32 v13, 31, v12
	s_waitcnt vmcnt(0)
	v_mad_i64_i32 v[0:1], s[20:21], s20, 3, v[12:13]
	v_mov_b64_e32 v[2:3], s[68:69]
	s_movk_i32 s42, 0xc00
	v_mad_u64_u32 v[2:3], s[20:21], v0, s42, v[2:3]
	v_mad_i32_i24 v3, v1, s42, v3
	v_lshlrev_b32_e32 v0, 2, v171
	v_mov_b32_e32 v1, v64
	v_lshl_add_u64 v[8:9], v[2:3], 0, v[0:1]
	global_load_dwordx4 v[178:181], v[8:9], off
	s_nop 0
	global_load_dwordx4 v[8:11], v[8:9], off offset:16
	s_waitcnt vmcnt(1)
	v_cvt_pk_bf16_f32 v178, v178, v179
	v_cvt_pk_bf16_f32 v179, v180, v181
	s_waitcnt vmcnt(0)
	v_cvt_pk_bf16_f32 v180, v8, v9
	v_cvt_pk_bf16_f32 v181, v10, v11
.LBB0_177:
.LBB0_178:
	s_andn2_saveexec_b64 s[12:13], s[12:13]
	s_cbranch_execz .LBB0_182
	v_cmp_gt_u32_e32 vcc, s28, v6
	s_waitcnt vmcnt(0)
	v_mov_b32_e32 v181, 0
	v_mov_b32_e32 v180, 0
	v_mov_b32_e32 v179, 0
	v_mov_b32_e32 v178, 0
	s_and_saveexec_b64 s[20:21], vcc
	s_cbranch_execz .LBB0_181
	v_add_u32_e32 v0, s31, v6
	v_mad_i64_i32 v[0:1], s[42:43], v0, s97, v[4:5]
	v_readlane_b32 s42, v252, 0
	v_readlane_b32 s43, v252, 1
	s_nop 1
	v_lshl_add_u64 v[0:1], s[42:43], 1, v[0:1]
	global_load_dwordx4 v[178:181], v[0:1], off

.LBB0_182:
	s_or_b64 exec, exec, s[12:13]
	v_lshl_add_u32 v214, v12, 7, v170
.LBB0_183:
	s_or_b64 exec, exec, s[2:3]
	v_add_u32_e32 v0, 64, v66
	v_ashrrev_i32_e32 v14, 3, v0
	s_movk_i32 s2, 0x43
	v_cmp_gt_i32_e64 s[42:43], s2, v14
	s_and_saveexec_b64 s[2:3], s[42:43]
	s_cbranch_execz .LBB0_196
	v_add_u32_e32 v6, -3, v14
	v_cmp_gt_i32_e32 vcc, 3, v14
	s_and_saveexec_b64 s[12:13], vcc
	s_xor_b64 s[12:13], exec, s[12:13]
	s_cbranch_execz .LBB0_191
	s_cmp_gt_i32 s18, -1
	s_mov_b64 s[20:21], -1
	s_cbranch_scc1 .LBB0_188
	s_cmp_eq_u32 s17, 0
	s_cbranch_scc1 .LBB0_815
	v_add_u32_e32 v0, s31, v6
	v_mad_i64_i32 v[0:1], s[20:21], v0, s97, v[4:5]
	v_readlane_b32 s20, v252, 0
	v_readlane_b32 s21, v252, 1
	s_nop 1
	v_lshl_add_u64 v[0:1], s[20:21], 1, v[0:1]
	global_load_dwordx4 v[182:185], v[0:1], off
	s_mov_b64 s[20:21], 0

.LBB0_189:
	s_add_i32 s20, s18, s38
	v_ashrrev_i32_e32 v15, 31, v14
	s_waitcnt vmcnt(0)
	v_mad_i64_i32 v[0:1], s[20:21], s20, 3, v[14:15]
	v_mov_b64_e32 v[2:3], s[68:69]
	s_movk_i32 s44, 0xc00
	v_mad_u64_u32 v[2:3], s[20:21], v0, s44, v[2:3]
	v_mad_i32_i24 v3, v1, s44, v3
	v_lshlrev_b32_e32 v0, 2, v171
	v_mov_b32_e32 v1, v64
	v_lshl_add_u64 v[8:9], v[2:3], 0, v[0:1]
	global_load_dwordx4 v[182:185], v[8:9], off
	s_nop 0
	global_load_dwordx4 v[8:11], v[8:9], off offset:16
	s_waitcnt vmcnt(1)
	v_cvt_pk_bf16_f32 v182, v182, v183
	v_cvt_pk_bf16_f32 v183, v184, v185
	s_waitcnt vmcnt(0)
	v_cvt_pk_bf16_f32 v184, v8, v9
	v_cvt_pk_bf16_f32 v185, v10, v11
.LBB0_190:
.LBB0_191:
	s_andn2_saveexec_b64 s[12:13], s[12:13]
	s_cbranch_execz .LBB0_195
	v_cmp_gt_u32_e32 vcc, s28, v6
	v_mov_b32_e32 v185, 0
	v_mov_b32_e32 v184, 0
	v_mov_b32_e32 v183, 0
	v_mov_b32_e32 v182, 0
	s_and_saveexec_b64 s[20:21], vcc
	s_cbranch_execz .LBB0_194
	v_add_u32_e32 v0, s31, v6
	v_mad_i64_i32 v[0:1], s[44:45], v0, s97, v[4:5]
	v_readlane_b32 s44, v252, 0
	v_readlane_b32 s45, v252, 1
	s_nop 1
	v_lshl_add_u64 v[0:1], s[44:45], 1, v[0:1]
	global_load_dwordx4 v[182:185], v[0:1], off

.LBB0_195:
	s_or_b64 exec, exec, s[12:13]
	v_lshl_add_u32 v215, v14, 7, v170
.LBB0_196:
	s_or_b64 exec, exec, s[2:3]
	v_add_u32_e32 v0, 0x80, v66
	v_ashrrev_i32_e32 v16, 3, v0
	s_movk_i32 s2, 0x43
	v_cmp_gt_i32_e64 s[44:45], s2, v16
	s_and_saveexec_b64 s[2:3], s[44:45]
	s_cbranch_execz .LBB0_209
	v_add_u32_e32 v6, -3, v16
	v_cmp_gt_i32_e32 vcc, 3, v16
	s_and_saveexec_b64 s[12:13], vcc
	s_xor_b64 s[12:13], exec, s[12:13]
	s_cbranch_execz .LBB0_204
	s_cmp_gt_i32 s18, -1
	s_mov_b64 s[20:21], -1
	s_cbranch_scc1 .LBB0_201
	s_cmp_eq_u32 s17, 0
	s_cbranch_scc1 .LBB0_816
	v_add_u32_e32 v0, s31, v6
	v_mad_i64_i32 v[0:1], s[20:21], v0, s97, v[4:5]
	v_readlane_b32 s20, v252, 0
	v_readlane_b32 s21, v252, 1
	s_nop 1
	v_lshl_add_u64 v[0:1], s[20:21], 1, v[0:1]
	global_load_dwordx4 v[186:189], v[0:1], off
	s_mov_b64 s[20:21], 0

.LBB0_202:
	s_add_i32 s20, s18, s38
	v_ashrrev_i32_e32 v17, 31, v16
	s_waitcnt vmcnt(0)
	v_mad_i64_i32 v[0:1], s[20:21], s20, 3, v[16:17]
	v_mov_b64_e32 v[2:3], s[68:69]
	s_movk_i32 s46, 0xc00
	v_mad_u64_u32 v[2:3], s[20:21], v0, s46, v[2:3]
	v_mad_i32_i24 v3, v1, s46, v3
	v_lshlrev_b32_e32 v0, 2, v171
	v_mov_b32_e32 v1, v64
	v_lshl_add_u64 v[8:9], v[2:3], 0, v[0:1]
	global_load_dwordx4 v[186:189], v[8:9], off
	s_nop 0
	global_load_dwordx4 v[8:11], v[8:9], off offset:16
	s_waitcnt vmcnt(1)
	v_cvt_pk_bf16_f32 v186, v186, v187
	v_cvt_pk_bf16_f32 v187, v188, v189
	s_waitcnt vmcnt(0)
	v_cvt_pk_bf16_f32 v188, v8, v9
	v_cvt_pk_bf16_f32 v189, v10, v11
.LBB0_203:
.LBB0_204:
	s_andn2_saveexec_b64 s[12:13], s[12:13]
	s_cbranch_execz .LBB0_208
	v_cmp_gt_u32_e32 vcc, s28, v6
	v_mov_b32_e32 v189, 0
	v_mov_b32_e32 v188, 0
	v_mov_b32_e32 v187, 0
	v_mov_b32_e32 v186, 0
	s_and_saveexec_b64 s[20:21], vcc
	s_cbranch_execz .LBB0_207
	v_add_u32_e32 v0, s31, v6
	v_mad_i64_i32 v[0:1], s[46:47], v0, s97, v[4:5]
	v_readlane_b32 s46, v252, 0
	v_readlane_b32 s47, v252, 1
	s_nop 1
	v_lshl_add_u64 v[0:1], s[46:47], 1, v[0:1]
	global_load_dwordx4 v[186:189], v[0:1], off

.LBB0_208:
	s_or_b64 exec, exec, s[12:13]
	v_lshl_add_u32 v216, v16, 7, v170
.LBB0_209:
	s_or_b64 exec, exec, s[2:3]
	v_add_u32_e32 v0, 0xc0, v66
	v_ashrrev_i32_e32 v18, 3, v0
	s_movk_i32 s2, 0x43
	v_cmp_gt_i32_e64 s[46:47], s2, v18
	s_and_saveexec_b64 s[2:3], s[46:47]
	s_cbranch_execz .LBB0_222
	v_add_u32_e32 v6, -3, v18
	v_cmp_gt_i32_e32 vcc, 3, v18
	s_and_saveexec_b64 s[12:13], vcc
	s_xor_b64 s[12:13], exec, s[12:13]
	s_cbranch_execz .LBB0_217
	s_cmp_gt_i32 s18, -1
	s_mov_b64 s[20:21], -1
	s_cbranch_scc1 .LBB0_214
	s_cmp_eq_u32 s17, 0
	s_cbranch_scc1 .LBB0_817
	v_add_u32_e32 v0, s31, v6
	v_mad_i64_i32 v[0:1], s[20:21], v0, s97, v[4:5]
	v_readlane_b32 s20, v252, 0
	v_readlane_b32 s21, v252, 1
	s_nop 1
	v_lshl_add_u64 v[0:1], s[20:21], 1, v[0:1]
	global_load_dwordx4 v[190:193], v[0:1], off
	s_mov_b64 s[20:21], 0

.LBB0_215:
	s_add_i32 s20, s18, s38
	v_ashrrev_i32_e32 v19, 31, v18
	s_waitcnt vmcnt(0)
	v_mad_i64_i32 v[0:1], s[20:21], s20, 3, v[18:19]
	v_mov_b64_e32 v[2:3], s[68:69]
	s_movk_i32 s48, 0xc00
	v_mad_u64_u32 v[2:3], s[20:21], v0, s48, v[2:3]
	v_mad_i32_i24 v3, v1, s48, v3
	v_lshlrev_b32_e32 v0, 2, v171
	v_mov_b32_e32 v1, v64
	v_lshl_add_u64 v[8:9], v[2:3], 0, v[0:1]
	global_load_dwordx4 v[190:193], v[8:9], off
	s_nop 0
	global_load_dwordx4 v[8:11], v[8:9], off offset:16
	s_waitcnt vmcnt(1)
	v_cvt_pk_bf16_f32 v190, v190, v191
	v_cvt_pk_bf16_f32 v191, v192, v193
	s_waitcnt vmcnt(0)
	v_cvt_pk_bf16_f32 v192, v8, v9
	v_cvt_pk_bf16_f32 v193, v10, v11
.LBB0_216:
.LBB0_217:
	s_andn2_saveexec_b64 s[12:13], s[12:13]
	s_cbranch_execz .LBB0_221
	v_cmp_gt_u32_e32 vcc, s28, v6
	v_mov_b32_e32 v193, 0
	v_mov_b32_e32 v192, 0
	v_mov_b32_e32 v191, 0
	v_mov_b32_e32 v190, 0
	s_and_saveexec_b64 s[20:21], vcc
	s_cbranch_execz .LBB0_220
	v_add_u32_e32 v0, s31, v6
	v_mad_i64_i32 v[0:1], s[48:49], v0, s97, v[4:5]
	v_readlane_b32 s48, v252, 0
	v_readlane_b32 s49, v252, 1
	s_nop 1
	v_lshl_add_u64 v[0:1], s[48:49], 1, v[0:1]
	global_load_dwordx4 v[190:193], v[0:1], off

.LBB0_221:
	s_or_b64 exec, exec, s[12:13]
	v_lshl_add_u32 v217, v18, 7, v170
.LBB0_222:
	s_or_b64 exec, exec, s[2:3]
	v_add_u32_e32 v0, 0x100, v66
	v_ashrrev_i32_e32 v20, 3, v0
	s_movk_i32 s2, 0x43
	v_cmp_gt_i32_e64 s[48:49], s2, v20
	s_and_saveexec_b64 s[2:3], s[48:49]
	s_cbranch_execz .LBB0_235
	v_add_u32_e32 v6, -3, v20
	v_cmp_gt_i32_e32 vcc, 3, v20
	s_and_saveexec_b64 s[12:13], vcc
	s_xor_b64 s[12:13], exec, s[12:13]
	s_cbranch_execz .LBB0_230
	s_cmp_gt_i32 s18, -1
	s_mov_b64 s[20:21], -1
	s_cbranch_scc1 .LBB0_227
	s_cmp_eq_u32 s17, 0
	s_cbranch_scc1 .LBB0_818
	v_add_u32_e32 v0, s31, v6
	v_mad_i64_i32 v[0:1], s[20:21], v0, s97, v[4:5]
	v_readlane_b32 s20, v252, 0
	v_readlane_b32 s21, v252, 1
	s_nop 1
	v_lshl_add_u64 v[0:1], s[20:21], 1, v[0:1]
	global_load_dwordx4 v[194:197], v[0:1], off
	s_mov_b64 s[20:21], 0

.LBB0_228:
	s_add_i32 s20, s18, s38
	v_ashrrev_i32_e32 v21, 31, v20
	s_waitcnt vmcnt(0)
	v_mad_i64_i32 v[0:1], s[20:21], s20, 3, v[20:21]
	v_mov_b64_e32 v[2:3], s[68:69]
	s_movk_i32 s50, 0xc00
	v_mad_u64_u32 v[2:3], s[20:21], v0, s50, v[2:3]
	v_mad_i32_i24 v3, v1, s50, v3
	v_lshlrev_b32_e32 v0, 2, v171
	v_mov_b32_e32 v1, v64
	v_lshl_add_u64 v[8:9], v[2:3], 0, v[0:1]
	global_load_dwordx4 v[194:197], v[8:9], off
	s_nop 0
	global_load_dwordx4 v[8:11], v[8:9], off offset:16
	s_waitcnt vmcnt(1)
	v_cvt_pk_bf16_f32 v194, v194, v195
	v_cvt_pk_bf16_f32 v195, v196, v197
	s_waitcnt vmcnt(0)
	v_cvt_pk_bf16_f32 v196, v8, v9
	v_cvt_pk_bf16_f32 v197, v10, v11
.LBB0_229:
.LBB0_230:
	s_andn2_saveexec_b64 s[12:13], s[12:13]
	s_cbranch_execz .LBB0_234
	v_cmp_gt_u32_e32 vcc, s28, v6
	v_mov_b32_e32 v197, 0
	v_mov_b32_e32 v196, 0
	v_mov_b32_e32 v195, 0
	v_mov_b32_e32 v194, 0
	s_and_saveexec_b64 s[20:21], vcc
	s_cbranch_execz .LBB0_233
	v_add_u32_e32 v0, s31, v6
	v_mad_i64_i32 v[0:1], s[50:51], v0, s97, v[4:5]
	v_readlane_b32 s50, v252, 0
	v_readlane_b32 s51, v252, 1
	s_nop 1
	v_lshl_add_u64 v[0:1], s[50:51], 1, v[0:1]
	global_load_dwordx4 v[194:197], v[0:1], off

.LBB0_234:
	s_or_b64 exec, exec, s[12:13]
	v_lshl_add_u32 v218, v20, 7, v170
.LBB0_235:
	s_or_b64 exec, exec, s[2:3]
	v_add_u32_e32 v0, 0x140, v66
	v_ashrrev_i32_e32 v22, 3, v0
	s_movk_i32 s2, 0x43
	v_cmp_gt_i32_e64 s[50:51], s2, v22
	s_and_saveexec_b64 s[2:3], s[50:51]
	s_cbranch_execz .LBB0_248
	v_add_u32_e32 v6, -3, v22
	v_cmp_gt_i32_e32 vcc, 3, v22
	s_and_saveexec_b64 s[12:13], vcc
	s_xor_b64 s[12:13], exec, s[12:13]
	s_cbranch_execz .LBB0_243
	s_cmp_gt_i32 s18, -1
	s_mov_b64 s[20:21], -1
	s_cbranch_scc1 .LBB0_240
	s_cmp_eq_u32 s17, 0
	s_cbranch_scc1 .LBB0_819
	v_add_u32_e32 v0, s31, v6
	v_mad_i64_i32 v[0:1], s[20:21], v0, s97, v[4:5]
	v_readlane_b32 s20, v252, 0
	v_readlane_b32 s21, v252, 1
	s_nop 1
	v_lshl_add_u64 v[0:1], s[20:21], 1, v[0:1]
	global_load_dwordx4 v[198:201], v[0:1], off
	s_mov_b64 s[20:21], 0

.LBB0_241:
	s_add_i32 s20, s18, s38
	v_ashrrev_i32_e32 v23, 31, v22
	s_waitcnt vmcnt(0)
	v_mad_i64_i32 v[0:1], s[20:21], s20, 3, v[22:23]
	v_mov_b64_e32 v[2:3], s[68:69]
	s_movk_i32 s52, 0xc00
	v_mad_u64_u32 v[2:3], s[20:21], v0, s52, v[2:3]
	v_mad_i32_i24 v3, v1, s52, v3
	v_lshlrev_b32_e32 v0, 2, v171
	v_mov_b32_e32 v1, v64
	v_lshl_add_u64 v[8:9], v[2:3], 0, v[0:1]
	global_load_dwordx4 v[198:201], v[8:9], off
	s_nop 0
	global_load_dwordx4 v[8:11], v[8:9], off offset:16
	s_waitcnt vmcnt(1)
	v_cvt_pk_bf16_f32 v198, v198, v199
	v_cvt_pk_bf16_f32 v199, v200, v201
	s_waitcnt vmcnt(0)
	v_cvt_pk_bf16_f32 v200, v8, v9
	v_cvt_pk_bf16_f32 v201, v10, v11
.LBB0_242:
.LBB0_243:
	s_andn2_saveexec_b64 s[12:13], s[12:13]
	s_cbranch_execz .LBB0_247
	v_cmp_gt_u32_e32 vcc, s28, v6
	v_mov_b32_e32 v201, 0
	v_mov_b32_e32 v200, 0
	v_mov_b32_e32 v199, 0
	v_mov_b32_e32 v198, 0
	s_and_saveexec_b64 s[20:21], vcc
	s_cbranch_execz .LBB0_246
	v_add_u32_e32 v0, s31, v6
	v_mad_i64_i32 v[0:1], s[52:53], v0, s97, v[4:5]
	v_readlane_b32 s52, v252, 0
	v_readlane_b32 s53, v252, 1
	s_nop 1
	v_lshl_add_u64 v[0:1], s[52:53], 1, v[0:1]
	global_load_dwordx4 v[198:201], v[0:1], off

.LBB0_247:
	s_or_b64 exec, exec, s[12:13]
	v_lshl_add_u32 v219, v22, 7, v170
.LBB0_248:
	s_or_b64 exec, exec, s[2:3]
	v_add_u32_e32 v0, 0x180, v66
	v_ashrrev_i32_e32 v24, 3, v0
	s_movk_i32 s2, 0x43
	v_cmp_gt_i32_e64 s[52:53], s2, v24
	s_and_saveexec_b64 s[2:3], s[52:53]
	s_cbranch_execz .LBB0_261
	v_add_u32_e32 v6, -3, v24
	v_cmp_gt_i32_e32 vcc, 3, v24
	s_and_saveexec_b64 s[12:13], vcc
	s_xor_b64 s[12:13], exec, s[12:13]
	s_cbranch_execz .LBB0_256
	s_cmp_gt_i32 s18, -1
	s_mov_b64 s[20:21], -1
	s_cbranch_scc1 .LBB0_253
	s_cmp_eq_u32 s17, 0
	s_cbranch_scc1 .LBB0_820
	v_add_u32_e32 v0, s31, v6
	v_mad_i64_i32 v[0:1], s[20:21], v0, s97, v[4:5]
	v_readlane_b32 s20, v252, 0
	v_readlane_b32 s21, v252, 1
	s_nop 1
	v_lshl_add_u64 v[0:1], s[20:21], 1, v[0:1]
	global_load_dwordx4 v[202:205], v[0:1], off
	s_mov_b64 s[20:21], 0

.LBB0_254:
	s_add_i32 s20, s18, s38
	v_ashrrev_i32_e32 v25, 31, v24
	s_waitcnt vmcnt(0)
	v_mad_i64_i32 v[0:1], s[20:21], s20, 3, v[24:25]
	v_mov_b64_e32 v[2:3], s[68:69]
	s_movk_i32 s54, 0xc00
	v_mad_u64_u32 v[2:3], s[20:21], v0, s54, v[2:3]
	v_mad_i32_i24 v3, v1, s54, v3
	v_lshlrev_b32_e32 v0, 2, v171
	v_mov_b32_e32 v1, v64
	v_lshl_add_u64 v[8:9], v[2:3], 0, v[0:1]
	global_load_dwordx4 v[202:205], v[8:9], off
	s_nop 0
	global_load_dwordx4 v[8:11], v[8:9], off offset:16
	s_waitcnt vmcnt(1)
	v_cvt_pk_bf16_f32 v202, v202, v203
	v_cvt_pk_bf16_f32 v203, v204, v205
	s_waitcnt vmcnt(0)
	v_cvt_pk_bf16_f32 v204, v8, v9
	v_cvt_pk_bf16_f32 v205, v10, v11
.LBB0_255:
.LBB0_256:
	s_andn2_saveexec_b64 s[12:13], s[12:13]
	s_cbranch_execz .LBB0_260
	v_cmp_gt_u32_e32 vcc, s28, v6
	v_mov_b32_e32 v205, 0
	v_mov_b32_e32 v204, 0
	v_mov_b32_e32 v203, 0
	v_mov_b32_e32 v202, 0
	s_and_saveexec_b64 s[20:21], vcc
	s_cbranch_execz .LBB0_259
	v_add_u32_e32 v0, s31, v6
	v_mad_i64_i32 v[0:1], s[54:55], v0, s97, v[4:5]
	v_readlane_b32 s54, v252, 0
	v_readlane_b32 s55, v252, 1
	s_nop 1
	v_lshl_add_u64 v[0:1], s[54:55], 1, v[0:1]
	global_load_dwordx4 v[202:205], v[0:1], off

.LBB0_260:
	s_or_b64 exec, exec, s[12:13]
	v_lshl_add_u32 v228, v24, 7, v170
.LBB0_261:
	s_or_b64 exec, exec, s[2:3]
	v_add_u32_e32 v0, 0x1c0, v66
	v_ashrrev_i32_e32 v26, 3, v0
	s_movk_i32 s2, 0x43
	v_cmp_gt_i32_e64 s[54:55], s2, v26
	s_and_saveexec_b64 s[2:3], s[54:55]
	s_cbranch_execz .LBB0_274
	v_add_u32_e32 v6, -3, v26
	v_cmp_gt_i32_e32 vcc, 3, v26
	s_and_saveexec_b64 s[12:13], vcc
	s_xor_b64 s[12:13], exec, s[12:13]
	s_cbranch_execz .LBB0_269
	s_cmp_gt_i32 s18, -1
	s_mov_b64 s[20:21], -1
	s_cbranch_scc1 .LBB0_266
	s_cmp_eq_u32 s17, 0
	s_cbranch_scc1 .LBB0_821
	v_add_u32_e32 v0, s31, v6
	v_mad_i64_i32 v[0:1], s[20:21], v0, s97, v[4:5]
	v_readlane_b32 s20, v252, 0
	v_readlane_b32 s21, v252, 1
	s_nop 1
	v_lshl_add_u64 v[0:1], s[20:21], 1, v[0:1]
	global_load_dwordx4 v[206:209], v[0:1], off
	s_mov_b64 s[20:21], 0

.LBB0_267:
	s_add_i32 s20, s18, s38
	v_ashrrev_i32_e32 v27, 31, v26
	s_waitcnt vmcnt(0)
	v_mad_i64_i32 v[0:1], s[20:21], s20, 3, v[26:27]
	v_mov_b64_e32 v[2:3], s[68:69]
	s_movk_i32 s56, 0xc00
	v_mad_u64_u32 v[2:3], s[20:21], v0, s56, v[2:3]
	v_mad_i32_i24 v3, v1, s56, v3
	v_lshlrev_b32_e32 v0, 2, v171
	v_mov_b32_e32 v1, v64
	v_lshl_add_u64 v[8:9], v[2:3], 0, v[0:1]
	global_load_dwordx4 v[206:209], v[8:9], off
	s_nop 0
	global_load_dwordx4 v[8:11], v[8:9], off offset:16
	s_waitcnt vmcnt(1)
	v_cvt_pk_bf16_f32 v206, v206, v207
	v_cvt_pk_bf16_f32 v207, v208, v209
	s_waitcnt vmcnt(0)
	v_cvt_pk_bf16_f32 v208, v8, v9
	v_cvt_pk_bf16_f32 v209, v10, v11
.LBB0_268:
.LBB0_269:
	s_andn2_saveexec_b64 s[12:13], s[12:13]
	s_cbranch_execz .LBB0_273
	v_cmp_gt_u32_e32 vcc, s28, v6
	v_mov_b32_e32 v209, 0
	v_mov_b32_e32 v208, 0
	v_mov_b32_e32 v207, 0
	v_mov_b32_e32 v206, 0
	s_and_saveexec_b64 s[20:21], vcc
	s_cbranch_execz .LBB0_272
	v_add_u32_e32 v0, s31, v6
	v_mad_i64_i32 v[0:1], s[56:57], v0, s97, v[4:5]
	v_readlane_b32 s56, v252, 0
	v_readlane_b32 s57, v252, 1
	s_nop 1
	v_lshl_add_u64 v[0:1], s[56:57], 1, v[0:1]
	global_load_dwordx4 v[206:209], v[0:1], off

.LBB0_273:
	s_or_b64 exec, exec, s[12:13]
	v_lshl_add_u32 v229, v26, 7, v170

.LBB0_287:
	s_or_b64 exec, exec, s[2:3]
	s_waitcnt vmcnt(0)
	ds_write_b128 v214, v[178:181] offset:18432
	ds_write_b128 v215, v[182:185] offset:18432
	ds_write_b128 v216, v[186:189] offset:18432
	ds_write_b128 v217, v[190:193] offset:18432
	ds_write_b128 v218, v[194:197] offset:18432
	ds_write_b128 v219, v[198:201] offset:18432
	ds_write_b128 v228, v[202:205] offset:18432
	ds_write_b128 v229, v[206:209] offset:18432
	s_waitcnt vmcnt(0) lgkmcnt(0)
	s_cmp_lt_i32 s18, 0
	s_cselect_b64 s[20:21], -1, 0
	s_mov_b64 s[12:13], -1
	s_and_b64 vcc, exec, s[20:21]
	s_cbranch_vccz .LBB0_290
	s_mov_b64 s[12:13], 0
	s_cmp_lg_u32 s17, 63
	s_mov_b64 s[2:3], 0
	s_cbranch_scc1 .LBB0_290
	s_lshl_b32 s2, s29, 3
	s_add_i32 s2, s6, s2
	s_mul_hi_i32 s3, s2, 0x2400
	s_mulk_i32 s2, 0x2400
	s_add_u32 s2, s77, s2
	s_addc_u32 s3, s79, s3

.LBB0_297:
	s_andn2_b64 vcc, exec, s[12:13]
	v_lshl_add_u64 v[68:69], v[66:67], 1, s[2:3]
	v_readlane_b32 s13, v253, 34
	v_readlane_b32 s58, v253, 29
	v_readlane_b32 s12, v253, 31
	s_cbranch_vccnz .LBB0_425
	v_readlane_b32 s12, v253, 30
	s_nop 1
	v_mov_b32_e32 v13, s12
	ds_read_b128 v[34:37], v13 offset:36096
	s_mov_b64 s[12:13], 0x6000
	v_lshl_add_u64 v[32:33], v[68:69], 0, s[12:13]
	s_movk_i32 s12, 0x7000
	v_add_co_u32_e32 v30, vcc, s12, v68
	s_waitcnt lgkmcnt(0)
	v_mul_f32_e32 v0, v168, v34
	v_mul_f32_e32 v15, 0x3e000000, v0
	ds_read_b128 v[38:41], v13 offset:35584
	ds_read_b128 v[4:7], v13 offset:35600
	ds_read_b128 v[0:3], v13 offset:35616
	v_addc_co_u32_e32 v31, vcc, 0, v69, vcc
	s_waitcnt lgkmcnt(2)
	v_mul_f32_e32 v17, 0x3fb8aa3b, v38
	v_exp_f32_e32 v17, v17
	s_waitcnt lgkmcnt(1)
	v_mul_f32_e32 v4, 0x3fb8aa3b, v4
	v_exp_f32_e32 v4, v4
	v_mul_f32_e32 v5, 0x3fb8aa3b, v5
	v_mul_f32_e32 v15, v15, v17
	v_mul_f32_e32 v17, 0x3fb8aa3b, v39
	v_exp_f32_e32 v17, v17
	v_cvt_pk_bf16_f32 v15, v15, s0
	global_store_short v[30:31], v15, off offset:-4096
	v_mul_f32_e32 v15, v169, v35
	v_mul_f32_e32 v15, 0x3e000000, v15
	v_mul_f32_e32 v15, v15, v17
	v_mul_f32_e32 v17, 0x3fb8aa3b, v40
	v_exp_f32_e32 v17, v17
	v_cvt_pk_bf16_f32 v15, v15, s0
	global_store_short v[32:33], v15, off offset:128
	v_mul_f32_e32 v15, v166, v36
	v_mul_f32_e32 v15, 0x3e000000, v15
	v_mul_f32_e32 v15, v15, v17
	v_mul_f32_e32 v17, 0x3fb8aa3b, v41
	v_cvt_pk_bf16_f32 v15, v15, s0
	v_exp_f32_e32 v17, v17
	global_store_short v[32:33], v15, off offset:256
	v_mul_f32_e32 v15, v167, v37
	ds_read_b128 v[34:37], v13 offset:36112
	v_mul_f32_e32 v15, 0x3e000000, v15
	v_mul_f32_e32 v15, v15, v17
	v_cvt_pk_bf16_f32 v15, v15, s0
	global_store_short v[32:33], v15, off offset:384
	s_waitcnt lgkmcnt(0)
	v_mul_f32_e32 v15, v162, v34
	v_mul_f32_e32 v15, 0x3e000000, v15
	v_mul_f32_e32 v4, v15, v4
	v_exp_f32_e32 v5, v5
	v_cvt_pk_bf16_f32 v4, v4, s0
	global_store_short v[32:33], v4, off offset:512
	v_mul_f32_e32 v4, v163, v35
	v_mul_f32_e32 v4, 0x3e000000, v4
	v_mul_f32_e32 v4, v4, v5
	v_mul_f32_e32 v5, 0x3fb8aa3b, v6
	v_exp_f32_e32 v5, v5
	v_cvt_pk_bf16_f32 v4, v4, s0
	global_store_short v[32:33], v4, off offset:640
	v_mul_f32_e32 v4, v10, v36
	v_mul_f32_e32 v4, 0x3e000000, v4
	v_mul_f32_e32 v4, v4, v5
	v_mul_f32_e32 v5, 0x3fb8aa3b, v7
	v_exp_f32_e32 v5, v5
	v_cvt_pk_bf16_f32 v4, v4, s0
	global_store_short v[32:33], v4, off offset:768
	v_mul_f32_e32 v4, v11, v37
	v_mul_f32_e32 v4, 0x3e000000, v4
	v_mul_f32_e32 v4, v4, v5
	v_cvt_pk_bf16_f32 v4, v4, s0
	global_store_short v[32:33], v4, off offset:896
	ds_read_b128 v[4:7], v13 offset:36128
	v_mul_f32_e32 v0, 0x3fb8aa3b, v0
	v_exp_f32_e32 v0, v0
	v_mul_f32_e32 v1, 0x3fb8aa3b, v1
	v_exp_f32_e32 v1, v1
	s_waitcnt lgkmcnt(0)
	v_mul_f32_e32 v4, v8, v4
	v_mul_f32_e32 v4, 0x3e000000, v4
	v_mul_f32_e32 v0, v4, v0
	v_cvt_pk_bf16_f32 v0, v0, s0
	global_store_short v[32:33], v0, off offset:1024
	v_mul_f32_e32 v0, v9, v5
	v_mul_f32_e32 v0, 0x3e000000, v0
	v_mul_f32_e32 v0, v0, v1
	v_mul_f32_e32 v1, 0x3fb8aa3b, v2
	v_exp_f32_e32 v1, v1
	v_cvt_pk_bf16_f32 v0, v0, s0
	global_store_short v[32:33], v0, off offset:1152
	v_mul_f32_e32 v0, v164, v6
	v_mul_f32_e32 v0, 0x3e000000, v0
	v_mul_f32_e32 v0, v0, v1
	v_mul_f32_e32 v1, 0x3fb8aa3b, v3
	v_cvt_pk_bf16_f32 v0, v0, s0
	v_exp_f32_e32 v1, v1
	global_store_short v[32:33], v0, off offset:1280
	v_mul_f32_e32 v0, v165, v7
	ds_read_b128 v[4:7], v13 offset:36144
	v_mul_f32_e32 v0, 0x3e000000, v0
	v_mul_f32_e32 v0, v0, v1
	v_cvt_pk_bf16_f32 v0, v0, s0
	global_store_short v[32:33], v0, off offset:1408
	s_waitcnt lgkmcnt(0)
	v_mul_f32_e32 v0, v158, v4
	v_mul_f32_e32 v4, 0x3e000000, v0
	ds_read_b128 v[34:37], v13 offset:35632
	ds_read_b128 v[8:11], v13 offset:35648
	ds_read_b128 v[0:3], v13 offset:35664
	v_readlane_b32 s12, v255, 3
	v_readlane_b32 s13, v255, 4
	s_waitcnt lgkmcnt(2)
	v_mul_f32_e32 v15, 0x3fb8aa3b, v34
	v_exp_f32_e32 v15, v15
	s_waitcnt lgkmcnt(1)
	v_mul_f32_e32 v8, 0x3fb8aa3b, v8
	v_exp_f32_e32 v8, v8
	s_waitcnt lgkmcnt(0)
	v_mul_f32_e32 v0, 0x3fb8aa3b, v0
	v_mul_f32_e32 v4, v4, v15
	v_cvt_pk_bf16_f32 v4, v4, s0
	global_store_short v[32:33], v4, off offset:1536
	v_mul_f32_e32 v4, v159, v5
	v_mul_f32_e32 v5, 0x3fb8aa3b, v35
	v_exp_f32_e32 v5, v5
	v_mul_f32_e32 v4, 0x3e000000, v4
	v_exp_f32_e32 v0, v0
	v_mul_f32_e32 v1, 0x3fb8aa3b, v1
	v_mul_f32_e32 v4, v4, v5
	v_mul_f32_e32 v5, 0x3fb8aa3b, v36
	v_exp_f32_e32 v5, v5
	v_cvt_pk_bf16_f32 v4, v4, s0
	global_store_short v[32:33], v4, off offset:1664
	v_mul_f32_e32 v4, v156, v6
	v_mul_f32_e32 v4, 0x3e000000, v4
	v_mul_f32_e32 v4, v4, v5
	v_mul_f32_e32 v5, 0x3fb8aa3b, v37
	v_exp_f32_e32 v5, v5
	v_cvt_pk_bf16_f32 v4, v4, s0
	global_store_short v[32:33], v4, off offset:1792
	v_mul_f32_e32 v4, v157, v7
	v_mul_f32_e32 v4, 0x3e000000, v4
	v_mul_f32_e32 v4, v4, v5
	v_cvt_pk_bf16_f32 v4, v4, s0
	global_store_short v[32:33], v4, off offset:1920
	ds_read_b128 v[4:7], v13 offset:36160
	v_exp_f32_e32 v1, v1
	s_waitcnt lgkmcnt(0)
	v_mul_f32_e32 v4, v144, v4
	v_mul_f32_e32 v4, 0x3e000000, v4
	v_mul_f32_e32 v4, v4, v8
	v_cvt_pk_bf16_f32 v4, v4, s0
	global_store_short v[32:33], v4, off offset:2048
	v_mul_f32_e32 v4, v145, v5
	v_mul_f32_e32 v5, 0x3fb8aa3b, v9
	v_exp_f32_e32 v5, v5
	v_mul_f32_e32 v4, 0x3e000000, v4
	v_mul_f32_e32 v4, v4, v5
	v_mul_f32_e32 v5, 0x3fb8aa3b, v10
	v_exp_f32_e32 v5, v5
	v_cvt_pk_bf16_f32 v4, v4, s0
	global_store_short v[32:33], v4, off offset:2176
	v_mul_f32_e32 v4, v160, v6
	v_mul_f32_e32 v4, 0x3e000000, v4
	v_mul_f32_e32 v4, v4, v5
	v_mul_f32_e32 v5, 0x3fb8aa3b, v11
	v_exp_f32_e32 v5, v5
	v_cvt_pk_bf16_f32 v4, v4, s0
	global_store_short v[32:33], v4, off offset:2304
	v_mul_f32_e32 v4, v161, v7
	v_mul_f32_e32 v4, 0x3e000000, v4
	v_mul_f32_e32 v4, v4, v5
	v_cvt_pk_bf16_f32 v4, v4, s0
	global_store_short v[32:33], v4, off offset:2432
	ds_read_b128 v[4:7], v13 offset:36176
	s_waitcnt lgkmcnt(0)
	v_mul_f32_e32 v4, v140, v4
	v_mul_f32_e32 v4, 0x3e000000, v4
	v_mul_f32_e32 v0, v4, v0
	v_cvt_pk_bf16_f32 v0, v0, s0
	global_store_short v[32:33], v0, off offset:2560
	v_mul_f32_e32 v0, v141, v5
	v_mul_f32_e32 v0, 0x3e000000, v0
	v_mul_f32_e32 v0, v0, v1
	v_mul_f32_e32 v1, 0x3fb8aa3b, v2
	v_exp_f32_e32 v1, v1
	v_cvt_pk_bf16_f32 v0, v0, s0
	global_store_short v[32:33], v0, off offset:2688
	v_mul_f32_e32 v0, v138, v6
	v_mul_f32_e32 v0, 0x3e000000, v0
	v_mul_f32_e32 v0, v0, v1
	v_mul_f32_e32 v1, 0x3fb8aa3b, v3
	v_exp_f32_e32 v1, v1
	v_cvt_pk_bf16_f32 v0, v0, s0
	global_store_short v[32:33], v0, off offset:2816
	v_mul_f32_e32 v0, v139, v7
	v_mul_f32_e32 v0, 0x3e000000, v0
	v_mul_f32_e32 v0, v0, v1
	v_cvt_pk_bf16_f32 v0, v0, s0
	global_store_short v[32:33], v0, off offset:2944
	ds_read_b128 v[0:3], v13 offset:36192
	ds_read_b128 v[4:7], v13 offset:35680
	s_waitcnt lgkmcnt(1)
	v_mul_f32_e32 v0, v136, v0
	s_waitcnt lgkmcnt(0)
	v_mul_f32_e32 v4, 0x3fb8aa3b, v4
	v_exp_f32_e32 v4, v4
	v_mul_f32_e32 v0, 0x3e000000, v0
	v_mul_f32_e32 v0, v0, v4
	v_cvt_pk_bf16_f32 v0, v0, s0
	global_store_short v[32:33], v0, off offset:3072
	v_mul_f32_e32 v0, v137, v1
	v_mul_f32_e32 v1, 0x3fb8aa3b, v5
	v_exp_f32_e32 v1, v1
	v_mul_f32_e32 v0, 0x3e000000, v0
	v_mul_f32_e32 v0, v0, v1
	v_mul_f32_e32 v1, 0x3fb8aa3b, v6
	v_exp_f32_e32 v1, v1
	v_cvt_pk_bf16_f32 v0, v0, s0
	global_store_short v[32:33], v0, off offset:3200
	v_mul_f32_e32 v0, v142, v2
	v_mul_f32_e32 v0, 0x3e000000, v0
	v_mul_f32_e32 v0, v0, v1
	v_mul_f32_e32 v1, 0x3fb8aa3b, v7
	v_exp_f32_e32 v1, v1
	v_cvt_pk_bf16_f32 v0, v0, s0
	global_store_short v[32:33], v0, off offset:3328
	v_mul_f32_e32 v0, v143, v3
	v_mul_f32_e32 v0, 0x3e000000, v0
	v_mul_f32_e32 v0, v0, v1
	v_cvt_pk_bf16_f32 v0, v0, s0
	global_store_short v[32:33], v0, off offset:3456
	ds_read_b128 v[0:3], v13 offset:36208
	ds_read_b128 v[4:7], v13 offset:35696
	s_waitcnt lgkmcnt(1)
	v_mul_f32_e32 v0, v132, v0
	s_waitcnt lgkmcnt(0)
	v_mul_f32_e32 v4, 0x3fb8aa3b, v4
	v_exp_f32_e32 v4, v4
	v_mul_f32_e32 v0, 0x3e000000, v0
	v_mul_f32_e32 v0, v0, v4
	v_cvt_pk_bf16_f32 v0, v0, s0
	global_store_short v[32:33], v0, off offset:3584
	v_mul_f32_e32 v0, v133, v1
	v_mul_f32_e32 v1, 0x3fb8aa3b, v5
	v_exp_f32_e32 v1, v1
	v_mul_f32_e32 v0, 0x3e000000, v0
	v_mul_f32_e32 v0, v0, v1
	v_mul_f32_e32 v1, 0x3fb8aa3b, v6
	v_exp_f32_e32 v1, v1
	v_cvt_pk_bf16_f32 v0, v0, s0
	global_store_short v[32:33], v0, off offset:3712
	v_mul_f32_e32 v0, v130, v2
	v_mul_f32_e32 v0, 0x3e000000, v0
	v_mul_f32_e32 v0, v0, v1
	v_mul_f32_e32 v1, 0x3fb8aa3b, v7
	v_exp_f32_e32 v1, v1
	v_cvt_pk_bf16_f32 v0, v0, s0
	global_store_short v[32:33], v0, off offset:3840
	v_mul_f32_e32 v0, v131, v3
	v_mul_f32_e32 v0, 0x3e000000, v0
	v_mul_f32_e32 v0, v0, v1
	v_cvt_pk_bf16_f32 v0, v0, s0
	global_store_short v[32:33], v0, off offset:3968
	ds_read_b128 v[0:3], v13 offset:36224
	ds_read_b128 v[4:7], v13 offset:35712
	s_waitcnt lgkmcnt(1)
	v_mul_f32_e32 v0, v128, v0
	s_waitcnt lgkmcnt(0)
	v_mul_f32_e32 v4, 0x3fb8aa3b, v4
	v_exp_f32_e32 v4, v4
	v_mul_f32_e32 v0, 0x3e000000, v0
	v_mul_f32_e32 v0, v0, v4
	v_cvt_pk_bf16_f32 v0, v0, s0
	global_store_short v[30:31], v0, off
	v_mul_f32_e32 v0, v129, v1
	v_mul_f32_e32 v1, 0x3fb8aa3b, v5
	v_exp_f32_e32 v1, v1
	v_mul_f32_e32 v0, 0x3e000000, v0
	v_mul_f32_e32 v0, v0, v1
	v_mul_f32_e32 v1, 0x3fb8aa3b, v6
	v_exp_f32_e32 v1, v1
	v_cvt_pk_bf16_f32 v0, v0, s0
	global_store_short v[30:31], v0, off offset:128
	v_mul_f32_e32 v0, v134, v2
	v_mul_f32_e32 v0, 0x3e000000, v0
	v_mul_f32_e32 v0, v0, v1
	v_mul_f32_e32 v1, 0x3fb8aa3b, v7
	v_exp_f32_e32 v1, v1
	v_cvt_pk_bf16_f32 v0, v0, s0
	global_store_short v[30:31], v0, off offset:256
	v_mul_f32_e32 v0, v135, v3
	v_mul_f32_e32 v0, 0x3e000000, v0
	v_mul_f32_e32 v0, v0, v1
	v_cvt_pk_bf16_f32 v0, v0, s0
	global_store_short v[30:31], v0, off offset:384
	ds_read_b128 v[0:3], v13 offset:36240
	ds_read_b128 v[4:7], v13 offset:35728
	s_waitcnt lgkmcnt(1)
	v_mul_f32_e32 v0, v124, v0
	s_waitcnt lgkmcnt(0)
	v_mul_f32_e32 v4, 0x3fb8aa3b, v4
	v_exp_f32_e32 v4, v4
	v_mul_f32_e32 v0, 0x3e000000, v0
	v_mul_f32_e32 v0, v0, v4
	v_cvt_pk_bf16_f32 v0, v0, s0
	global_store_short v[30:31], v0, off offset:512
	v_mul_f32_e32 v0, v125, v1
	v_mul_f32_e32 v1, 0x3fb8aa3b, v5
	v_exp_f32_e32 v1, v1
	v_mul_f32_e32 v0, 0x3e000000, v0
	v_mul_f32_e32 v0, v0, v1
	v_mul_f32_e32 v1, 0x3fb8aa3b, v6
	v_exp_f32_e32 v1, v1
	v_cvt_pk_bf16_f32 v0, v0, s0
	global_store_short v[30:31], v0, off offset:640
	v_mul_f32_e32 v0, v122, v2
	v_mul_f32_e32 v0, 0x3e000000, v0
	v_mul_f32_e32 v0, v0, v1
	v_mul_f32_e32 v1, 0x3fb8aa3b, v7
	v_exp_f32_e32 v1, v1
	v_cvt_pk_bf16_f32 v0, v0, s0
	global_store_short v[30:31], v0, off offset:768
	v_mul_f32_e32 v0, v123, v3
	v_mul_f32_e32 v0, 0x3e000000, v0
	v_mul_f32_e32 v0, v0, v1
	v_cvt_pk_bf16_f32 v0, v0, s0
	global_store_short v[30:31], v0, off offset:896
	ds_read_b128 v[0:3], v13 offset:36256
	ds_read_b128 v[4:7], v13 offset:35744
	s_waitcnt lgkmcnt(1)
	v_mul_f32_e32 v0, v120, v0
	s_waitcnt lgkmcnt(0)
	v_mul_f32_e32 v4, 0x3fb8aa3b, v4
	v_exp_f32_e32 v4, v4
	v_mul_f32_e32 v0, 0x3e000000, v0
	v_mul_f32_e32 v0, v0, v4
	v_cvt_pk_bf16_f32 v0, v0, s0
	global_store_short v[30:31], v0, off offset:1024
	v_mul_f32_e32 v0, v121, v1
	v_mul_f32_e32 v1, 0x3fb8aa3b, v5
	v_exp_f32_e32 v1, v1
	v_mul_f32_e32 v0, 0x3e000000, v0
	v_mul_f32_e32 v0, v0, v1
	v_mul_f32_e32 v1, 0x3fb8aa3b, v6
	v_exp_f32_e32 v1, v1
	v_cvt_pk_bf16_f32 v0, v0, s0
	global_store_short v[30:31], v0, off offset:1152
	v_mul_f32_e32 v0, v126, v2
	v_mul_f32_e32 v0, 0x3e000000, v0
	v_mul_f32_e32 v0, v0, v1
	v_mul_f32_e32 v1, 0x3fb8aa3b, v7
	v_exp_f32_e32 v1, v1
	v_cvt_pk_bf16_f32 v0, v0, s0
	global_store_short v[30:31], v0, off offset:1280
	v_mul_f32_e32 v0, v127, v3
	v_mul_f32_e32 v0, 0x3e000000, v0
	v_mul_f32_e32 v0, v0, v1
	v_cvt_pk_bf16_f32 v0, v0, s0
	global_store_short v[30:31], v0, off offset:1408
	ds_read_b128 v[0:3], v13 offset:36272
	ds_read_b128 v[4:7], v13 offset:35760
	s_waitcnt lgkmcnt(1)
	v_mul_f32_e32 v0, v116, v0
	s_waitcnt lgkmcnt(0)
	v_mul_f32_e32 v4, 0x3fb8aa3b, v4
	v_exp_f32_e32 v4, v4
	v_mul_f32_e32 v0, 0x3e000000, v0
	v_mul_f32_e32 v0, v0, v4
	v_cvt_pk_bf16_f32 v0, v0, s0
	global_store_short v[30:31], v0, off offset:1536
	v_mul_f32_e32 v0, v117, v1
	v_mul_f32_e32 v1, 0x3fb8aa3b, v5
	v_exp_f32_e32 v1, v1
	v_mul_f32_e32 v0, 0x3e000000, v0
	v_mul_f32_e32 v0, v0, v1
	v_mul_f32_e32 v1, 0x3fb8aa3b, v6
	v_exp_f32_e32 v1, v1
	v_cvt_pk_bf16_f32 v0, v0, s0
	global_store_short v[30:31], v0, off offset:1664
	v_mul_f32_e32 v0, v114, v2
	v_mul_f32_e32 v0, 0x3e000000, v0
	v_mul_f32_e32 v0, v0, v1
	v_mul_f32_e32 v1, 0x3fb8aa3b, v7
	v_exp_f32_e32 v1, v1
	v_cvt_pk_bf16_f32 v0, v0, s0
	global_store_short v[30:31], v0, off offset:1792
	v_mul_f32_e32 v0, v115, v3
	v_mul_f32_e32 v0, 0x3e000000, v0
	v_mul_f32_e32 v0, v0, v1
	v_cvt_pk_bf16_f32 v0, v0, s0
	global_store_short v[30:31], v0, off offset:1920
	ds_read_b128 v[0:3], v13 offset:36288
	ds_read_b128 v[4:7], v13 offset:35776
	s_waitcnt lgkmcnt(1)
	v_mul_f32_e32 v0, v112, v0
	s_waitcnt lgkmcnt(0)
	v_mul_f32_e32 v4, 0x3fb8aa3b, v4
	v_exp_f32_e32 v4, v4
	v_mul_f32_e32 v0, 0x3e000000, v0
	v_mul_f32_e32 v0, v0, v4
	v_cvt_pk_bf16_f32 v0, v0, s0
	global_store_short v[30:31], v0, off offset:2048
	v_mul_f32_e32 v0, v113, v1
	v_mul_f32_e32 v1, 0x3fb8aa3b, v5
	v_exp_f32_e32 v1, v1
	v_mul_f32_e32 v0, 0x3e000000, v0
	v_mul_f32_e32 v0, v0, v1
	v_mul_f32_e32 v1, 0x3fb8aa3b, v6
	v_exp_f32_e32 v1, v1
	v_cvt_pk_bf16_f32 v0, v0, s0
	global_store_short v[30:31], v0, off offset:2176
	v_mul_f32_e32 v0, v118, v2
	v_mul_f32_e32 v0, 0x3e000000, v0
	v_mul_f32_e32 v0, v0, v1
	v_mul_f32_e32 v1, 0x3fb8aa3b, v7
	v_exp_f32_e32 v1, v1
	v_cvt_pk_bf16_f32 v0, v0, s0
	global_store_short v[30:31], v0, off offset:2304
	v_mul_f32_e32 v0, v119, v3
	v_mul_f32_e32 v0, 0x3e000000, v0
	v_mul_f32_e32 v0, v0, v1
	v_cvt_pk_bf16_f32 v0, v0, s0
	global_store_short v[30:31], v0, off offset:2432
	ds_read_b128 v[0:3], v13 offset:36304
	ds_read_b128 v[4:7], v13 offset:35792
	s_waitcnt lgkmcnt(1)
	v_mul_f32_e32 v0, v110, v0
	s_waitcnt lgkmcnt(0)
	v_mul_f32_e32 v4, 0x3fb8aa3b, v4
	v_exp_f32_e32 v4, v4
	v_mul_f32_e32 v0, 0x3e000000, v0
	v_mul_f32_e32 v0, v0, v4
	v_cvt_pk_bf16_f32 v0, v0, s0
	global_store_short v[30:31], v0, off offset:2560
	v_mul_f32_e32 v0, v111, v1
	v_mul_f32_e32 v1, 0x3fb8aa3b, v5
	v_exp_f32_e32 v1, v1
	v_mul_f32_e32 v0, 0x3e000000, v0
	v_mul_f32_e32 v0, v0, v1
	v_mul_f32_e32 v1, 0x3fb8aa3b, v6
	v_exp_f32_e32 v1, v1
	v_cvt_pk_bf16_f32 v0, v0, s0
	global_store_short v[30:31], v0, off offset:2688
	v_mul_f32_e32 v0, v104, v2
	v_mul_f32_e32 v0, 0x3e000000, v0
	v_mul_f32_e32 v0, v0, v1
	v_mul_f32_e32 v1, 0x3fb8aa3b, v7
	v_exp_f32_e32 v1, v1
	v_cvt_pk_bf16_f32 v0, v0, s0
	global_store_short v[30:31], v0, off offset:2816
	v_mul_f32_e32 v0, v105, v3
	v_mul_f32_e32 v0, 0x3e000000, v0
	v_mul_f32_e32 v0, v0, v1
	v_cvt_pk_bf16_f32 v0, v0, s0
	global_store_short v[30:31], v0, off offset:2944
	ds_read_b128 v[0:3], v13 offset:36320
	ds_read_b128 v[4:7], v13 offset:35808
	s_waitcnt lgkmcnt(1)
	v_mul_f32_e32 v0, v108, v0
	s_waitcnt lgkmcnt(0)
	v_mul_f32_e32 v4, 0x3fb8aa3b, v4
	v_exp_f32_e32 v4, v4
	v_mul_f32_e32 v0, 0x3e000000, v0
	v_mul_f32_e32 v0, v0, v4
	v_cvt_pk_bf16_f32 v0, v0, s0
	global_store_short v[30:31], v0, off offset:3072
	v_mul_f32_e32 v0, v109, v1
	v_mul_f32_e32 v1, 0x3fb8aa3b, v5
	v_exp_f32_e32 v1, v1
	v_mul_f32_e32 v0, 0x3e000000, v0
	v_mul_f32_e32 v0, v0, v1
	v_mul_f32_e32 v1, 0x3fb8aa3b, v6
	v_exp_f32_e32 v1, v1
	v_cvt_pk_bf16_f32 v0, v0, s0
	global_store_short v[30:31], v0, off offset:3200
	v_mul_f32_e32 v0, v106, v2
	v_mul_f32_e32 v0, 0x3e000000, v0
	v_mul_f32_e32 v0, v0, v1
	v_mul_f32_e32 v1, 0x3fb8aa3b, v7
	v_exp_f32_e32 v1, v1
	v_cvt_pk_bf16_f32 v0, v0, s0
	global_store_short v[30:31], v0, off offset:3328
	v_mul_f32_e32 v0, v107, v3
	v_mul_f32_e32 v0, 0x3e000000, v0
	v_mul_f32_e32 v0, v0, v1
	v_cvt_pk_bf16_f32 v0, v0, s0
	global_store_short v[30:31], v0, off offset:3456
	ds_read_b128 v[0:3], v13 offset:36336
	ds_read_b128 v[4:7], v13 offset:35824
	s_waitcnt lgkmcnt(1)
	v_mul_f32_e32 v0, v102, v0
	s_waitcnt lgkmcnt(0)
	v_mul_f32_e32 v4, 0x3fb8aa3b, v4
	v_exp_f32_e32 v4, v4
	v_mul_f32_e32 v0, 0x3e000000, v0
	v_mul_f32_e32 v0, v0, v4
	v_cvt_pk_bf16_f32 v0, v0, s0
	global_store_short v[30:31], v0, off offset:3584
	v_mul_f32_e32 v0, v103, v1
	v_mul_f32_e32 v1, 0x3fb8aa3b, v5
	v_exp_f32_e32 v1, v1
	v_mul_f32_e32 v0, 0x3e000000, v0
	v_mul_f32_e32 v0, v0, v1
	v_mul_f32_e32 v1, 0x3fb8aa3b, v6
	v_exp_f32_e32 v1, v1
	v_cvt_pk_bf16_f32 v0, v0, s0
	global_store_short v[30:31], v0, off offset:3712
	v_mul_f32_e32 v0, v100, v2
	v_mul_f32_e32 v0, 0x3e000000, v0
	v_mul_f32_e32 v0, v0, v1
	v_mul_f32_e32 v1, 0x3fb8aa3b, v7
	v_exp_f32_e32 v1, v1
	v_cvt_pk_bf16_f32 v0, v0, s0
	global_store_short v[30:31], v0, off offset:3840
	v_mul_f32_e32 v0, v101, v3
	v_mul_f32_e32 v0, 0x3e000000, v0
	v_mul_f32_e32 v0, v0, v1
	v_cvt_pk_bf16_f32 v0, v0, s0
	global_store_short v[30:31], v0, off offset:3968
	v_lshlrev_b32_e32 v0, 1, v171
	v_mov_b32_e32 v1, v64
	v_lshl_add_u64 v[4:5], s[12:13], 0, v[0:1]
	s_and_saveexec_b64 s[12:13], s[40:41]
	s_cbranch_execz .LBB0_351
	v_add_u32_e32 v6, -3, v12
	v_cmp_gt_i32_e32 vcc, 3, v12
	s_and_saveexec_b64 s[40:41], vcc
	s_xor_b64 s[40:41], exec, s[40:41]
	s_cbranch_execz .LBB0_306
	s_mov_b64 s[58:59], -1
	s_and_b64 vcc, exec, s[20:21]
	s_cbranch_vccz .LBB0_303
	s_cmp_eq_u32 s17, 0
	s_cbranch_scc1 .LBB0_823
	v_add_u32_e32 v0, s31, v6
	v_mad_i64_i32 v[0:1], s[58:59], v0, s97, v[4:5]
	global_load_dwordx4 v[178:181], v[0:1], off
	s_mov_b64 s[58:59], 0

.LBB0_304:
	s_add_i32 s58, s18, s38
	v_ashrrev_i32_e32 v13, 31, v12
	s_waitcnt vmcnt(0)
	v_mad_i64_i32 v[0:1], s[58:59], s58, 3, v[12:13]
	v_readlane_b32 s58, v255, 7
	v_readlane_b32 s59, v255, 8
	s_mov_b32 s60, s77
	s_movk_i32 s77, 0xc00
	v_mov_b64_e32 v[2:3], s[58:59]
	v_mad_u64_u32 v[2:3], s[58:59], v0, s77, v[2:3]
	v_mad_i32_i24 v3, v1, s77, v3
	v_lshlrev_b32_e32 v0, 2, v171
	v_mov_b32_e32 v1, v64
	v_lshl_add_u64 v[6:7], v[2:3], 0, v[0:1]
	global_load_dwordx4 v[178:181], v[6:7], off offset:2048
	s_nop 0
	global_load_dwordx4 v[6:9], v[6:7], off offset:2064
	s_mov_b32 s77, s60
	s_waitcnt vmcnt(1)
	v_cvt_pk_bf16_f32 v178, v178, v179
	v_cvt_pk_bf16_f32 v179, v180, v181
	s_waitcnt vmcnt(0)
	v_cvt_pk_bf16_f32 v180, v6, v7
	v_cvt_pk_bf16_f32 v181, v8, v9
.LBB0_305:
.LBB0_306:
	s_andn2_saveexec_b64 s[40:41], s[40:41]
	s_cbranch_execz .LBB0_310
	s_mov_b32 s60, s79
	s_mov_b32 s80, s78
	v_cmp_gt_u32_e32 vcc, s28, v6
	s_waitcnt vmcnt(0)
	v_mov_b32_e32 v181, 0
	v_mov_b32_e32 v180, 0
	v_mov_b32_e32 v179, 0
	v_mov_b32_e32 v178, 0
	s_and_saveexec_b64 s[58:59], vcc
	s_cbranch_execz .LBB0_309
	v_add_u32_e32 v0, s31, v6
	v_mad_i64_i32 v[0:1], s[78:79], v0, s97, v[4:5]
	global_load_dwordx4 v[178:181], v[0:1], off

.LBB0_310:
	s_or_b64 exec, exec, s[40:41]
	v_lshl_add_u32 v214, v12, 7, v170
	s_or_b64 exec, exec, s[12:13]
	s_ashr_i32 s89, s88, 31
	s_and_saveexec_b64 s[40:41], s[42:43]
	s_cbranch_execnz .LBB0_352

.LBB0_312:
	v_add_u32_e32 v6, -3, v16
	v_cmp_gt_i32_e32 vcc, 3, v16
	s_and_saveexec_b64 s[12:13], vcc
	s_xor_b64 s[12:13], exec, s[12:13]
	s_cbranch_execz .LBB0_319
	s_andn2_b64 vcc, exec, s[20:21]
	s_mov_b64 s[42:43], -1
	s_cbranch_vccnz .LBB0_316
	s_cmp_eq_u32 s17, 0
	s_cbranch_scc1 .LBB0_824
	v_add_u32_e32 v0, s31, v6
	v_mad_i64_i32 v[0:1], s[42:43], v0, s97, v[4:5]
	global_load_dwordx4 v[182:185], v[0:1], off
	s_mov_b64 s[42:43], 0

.LBB0_317:
	s_add_i32 s42, s18, s38
	v_ashrrev_i32_e32 v17, 31, v16
	s_waitcnt vmcnt(0)
	v_mad_i64_i32 v[0:1], s[42:43], s42, 3, v[16:17]
	v_readlane_b32 s42, v255, 7
	v_readlane_b32 s43, v255, 8
	s_movk_i32 s44, 0xc00
	s_nop 0
	v_mov_b64_e32 v[2:3], s[42:43]
	v_mad_u64_u32 v[2:3], s[42:43], v0, s44, v[2:3]
	v_mad_i32_i24 v3, v1, s44, v3
	v_lshlrev_b32_e32 v0, 2, v171
	v_mov_b32_e32 v1, v64
	v_lshl_add_u64 v[6:7], v[2:3], 0, v[0:1]
	global_load_dwordx4 v[182:185], v[6:7], off offset:2048
	s_nop 0
	global_load_dwordx4 v[6:9], v[6:7], off offset:2064
	s_waitcnt vmcnt(1)
	v_cvt_pk_bf16_f32 v182, v182, v183
	v_cvt_pk_bf16_f32 v183, v184, v185
	s_waitcnt vmcnt(0)
	v_cvt_pk_bf16_f32 v184, v6, v7
	v_cvt_pk_bf16_f32 v185, v8, v9
.LBB0_318:
.LBB0_319:
	s_andn2_saveexec_b64 s[12:13], s[12:13]
	s_cbranch_execz .LBB0_323
	v_cmp_gt_u32_e32 vcc, s28, v6
	v_mov_b32_e32 v185, 0
	v_mov_b32_e32 v184, 0
	v_mov_b32_e32 v183, 0
	v_mov_b32_e32 v182, 0
	s_and_saveexec_b64 s[42:43], vcc
	s_cbranch_execz .LBB0_322
	v_add_u32_e32 v0, s31, v6
	v_mad_i64_i32 v[0:1], s[44:45], v0, s97, v[4:5]
	global_load_dwordx4 v[182:185], v[0:1], off

.LBB0_323:
	s_or_b64 exec, exec, s[12:13]
	v_lshl_add_u32 v215, v16, 7, v170
	s_or_b64 exec, exec, s[40:41]
	s_and_saveexec_b64 s[40:41], s[46:47]
	s_cbranch_execnz .LBB0_365

.LBB0_325:
	v_add_u32_e32 v6, -3, v20
	v_cmp_gt_i32_e32 vcc, 3, v20
	s_and_saveexec_b64 s[12:13], vcc
	s_xor_b64 s[12:13], exec, s[12:13]
	s_cbranch_execz .LBB0_332
	s_andn2_b64 vcc, exec, s[20:21]
	s_mov_b64 s[42:43], -1
	s_cbranch_vccnz .LBB0_329
	s_cmp_eq_u32 s17, 0
	s_cbranch_scc1 .LBB0_825
	v_add_u32_e32 v0, s31, v6
	v_mad_i64_i32 v[0:1], s[42:43], v0, s97, v[4:5]
	global_load_dwordx4 v[186:189], v[0:1], off
	s_mov_b64 s[42:43], 0

.LBB0_330:
	s_add_i32 s42, s18, s38
	v_ashrrev_i32_e32 v21, 31, v20
	s_waitcnt vmcnt(0)
	v_mad_i64_i32 v[0:1], s[42:43], s42, 3, v[20:21]
	v_readlane_b32 s42, v255, 7
	v_readlane_b32 s43, v255, 8
	s_movk_i32 s44, 0xc00
	s_nop 0
	v_mov_b64_e32 v[2:3], s[42:43]
	v_mad_u64_u32 v[2:3], s[42:43], v0, s44, v[2:3]
	v_mad_i32_i24 v3, v1, s44, v3
	v_lshlrev_b32_e32 v0, 2, v171
	v_mov_b32_e32 v1, v64
	v_lshl_add_u64 v[6:7], v[2:3], 0, v[0:1]
	global_load_dwordx4 v[186:189], v[6:7], off offset:2048
	s_nop 0
	global_load_dwordx4 v[6:9], v[6:7], off offset:2064
	s_waitcnt vmcnt(1)
	v_cvt_pk_bf16_f32 v186, v186, v187
	v_cvt_pk_bf16_f32 v187, v188, v189
	s_waitcnt vmcnt(0)
	v_cvt_pk_bf16_f32 v188, v6, v7
	v_cvt_pk_bf16_f32 v189, v8, v9
.LBB0_331:
.LBB0_332:
	s_andn2_saveexec_b64 s[12:13], s[12:13]
	s_cbranch_execz .LBB0_336
	v_cmp_gt_u32_e32 vcc, s28, v6
	v_mov_b32_e32 v189, 0
	v_mov_b32_e32 v188, 0
	v_mov_b32_e32 v187, 0
	v_mov_b32_e32 v186, 0
	s_and_saveexec_b64 s[42:43], vcc
	s_cbranch_execz .LBB0_335
	v_add_u32_e32 v0, s31, v6
	v_mad_i64_i32 v[0:1], s[44:45], v0, s97, v[4:5]
	global_load_dwordx4 v[186:189], v[0:1], off

.LBB0_336:
	s_or_b64 exec, exec, s[12:13]
	v_lshl_add_u32 v216, v20, 7, v170
	s_or_b64 exec, exec, s[40:41]
	s_and_saveexec_b64 s[40:41], s[50:51]
	s_cbranch_execnz .LBB0_378

.LBB0_338:
	v_add_u32_e32 v6, -3, v24
	v_cmp_gt_i32_e32 vcc, 3, v24
	s_and_saveexec_b64 s[12:13], vcc
	s_xor_b64 s[12:13], exec, s[12:13]
	s_cbranch_execz .LBB0_345
	s_andn2_b64 vcc, exec, s[20:21]
	s_mov_b64 s[42:43], -1
	s_cbranch_vccnz .LBB0_342
	s_cmp_eq_u32 s17, 0
	s_cbranch_scc1 .LBB0_826
	v_add_u32_e32 v0, s31, v6
	v_mad_i64_i32 v[0:1], s[42:43], v0, s97, v[4:5]
	global_load_dwordx4 v[190:193], v[0:1], off
	s_mov_b64 s[42:43], 0

.LBB0_343:
	s_add_i32 s42, s18, s38
	v_ashrrev_i32_e32 v25, 31, v24
	s_waitcnt vmcnt(0)
	v_mad_i64_i32 v[0:1], s[42:43], s42, 3, v[24:25]
	v_readlane_b32 s42, v255, 7
	v_readlane_b32 s43, v255, 8
	s_movk_i32 s44, 0xc00
	s_nop 0
	v_mov_b64_e32 v[2:3], s[42:43]
	v_mad_u64_u32 v[2:3], s[42:43], v0, s44, v[2:3]
	v_mad_i32_i24 v3, v1, s44, v3
	v_lshlrev_b32_e32 v0, 2, v171
	v_mov_b32_e32 v1, v64
	v_lshl_add_u64 v[6:7], v[2:3], 0, v[0:1]
	global_load_dwordx4 v[190:193], v[6:7], off offset:2048
	s_nop 0
	global_load_dwordx4 v[6:9], v[6:7], off offset:2064
	s_waitcnt vmcnt(1)
	v_cvt_pk_bf16_f32 v190, v190, v191
	v_cvt_pk_bf16_f32 v191, v192, v193
	s_waitcnt vmcnt(0)
	v_cvt_pk_bf16_f32 v192, v6, v7
	v_cvt_pk_bf16_f32 v193, v8, v9
.LBB0_344:
.LBB0_345:
	s_andn2_saveexec_b64 s[12:13], s[12:13]
	s_cbranch_execz .LBB0_349
	v_cmp_gt_u32_e32 vcc, s28, v6
	v_mov_b32_e32 v193, 0
	v_mov_b32_e32 v192, 0
	v_mov_b32_e32 v191, 0
	v_mov_b32_e32 v190, 0
	s_and_saveexec_b64 s[42:43], vcc
	s_cbranch_execz .LBB0_348
	v_add_u32_e32 v0, s31, v6
	v_mad_i64_i32 v[0:1], s[44:45], v0, s97, v[4:5]
	global_load_dwordx4 v[190:193], v[0:1], off

.LBB0_349:
	s_or_b64 exec, exec, s[12:13]
	v_lshl_add_u32 v217, v24, 7, v170
	s_or_b64 exec, exec, s[40:41]
	s_and_saveexec_b64 s[40:41], s[54:55]
	s_cbranch_execnz .LBB0_391

.LBB0_352:
	v_add_u32_e32 v6, -3, v14
	v_cmp_gt_i32_e32 vcc, 3, v14
	s_and_saveexec_b64 s[12:13], vcc
	s_xor_b64 s[12:13], exec, s[12:13]
	s_cbranch_execz .LBB0_359
	s_andn2_b64 vcc, exec, s[20:21]
	s_mov_b64 s[42:43], -1
	s_cbranch_vccnz .LBB0_356
	s_cmp_eq_u32 s17, 0
	s_cbranch_scc1 .LBB0_827
	v_add_u32_e32 v0, s31, v6
	v_mad_i64_i32 v[0:1], s[42:43], v0, s97, v[4:5]
	global_load_dwordx4 v[194:197], v[0:1], off
	s_mov_b64 s[42:43], 0

.LBB0_357:
	s_add_i32 s42, s18, s38
	v_ashrrev_i32_e32 v15, 31, v14
	s_waitcnt vmcnt(0)
	v_mad_i64_i32 v[0:1], s[42:43], s42, 3, v[14:15]
	v_readlane_b32 s42, v255, 7
	v_readlane_b32 s43, v255, 8
	s_movk_i32 s58, 0xc00
	s_nop 0
	v_mov_b64_e32 v[2:3], s[42:43]
	v_mad_u64_u32 v[2:3], s[42:43], v0, s58, v[2:3]
	v_mad_i32_i24 v3, v1, s58, v3
	v_lshlrev_b32_e32 v0, 2, v171
	v_mov_b32_e32 v1, v64
	v_lshl_add_u64 v[6:7], v[2:3], 0, v[0:1]
	global_load_dwordx4 v[194:197], v[6:7], off offset:2048
	s_nop 0
	global_load_dwordx4 v[6:9], v[6:7], off offset:2064
	s_waitcnt vmcnt(1)
	v_cvt_pk_bf16_f32 v194, v194, v195
	v_cvt_pk_bf16_f32 v195, v196, v197
	s_waitcnt vmcnt(0)
	v_cvt_pk_bf16_f32 v196, v6, v7
	v_cvt_pk_bf16_f32 v197, v8, v9
.LBB0_358:
.LBB0_359:
	s_andn2_saveexec_b64 s[12:13], s[12:13]
	s_cbranch_execz .LBB0_363
	v_cmp_gt_u32_e32 vcc, s28, v6
	v_mov_b32_e32 v197, 0
	v_mov_b32_e32 v196, 0
	v_mov_b32_e32 v195, 0
	v_mov_b32_e32 v194, 0
	s_and_saveexec_b64 s[42:43], vcc
	s_cbranch_execz .LBB0_362
	v_add_u32_e32 v0, s31, v6
	v_mad_i64_i32 v[0:1], s[58:59], v0, s97, v[4:5]
	global_load_dwordx4 v[194:197], v[0:1], off

.LBB0_363:
	s_or_b64 exec, exec, s[12:13]
	v_lshl_add_u32 v218, v14, 7, v170
	s_or_b64 exec, exec, s[40:41]
	s_and_saveexec_b64 s[40:41], s[44:45]
	s_cbranch_execnz .LBB0_312

.LBB0_365:
	v_add_u32_e32 v6, -3, v18
	v_cmp_gt_i32_e32 vcc, 3, v18
	s_and_saveexec_b64 s[12:13], vcc
	s_xor_b64 s[12:13], exec, s[12:13]
	s_cbranch_execz .LBB0_372
	s_andn2_b64 vcc, exec, s[20:21]
	s_mov_b64 s[42:43], -1
	s_cbranch_vccnz .LBB0_369
	s_cmp_eq_u32 s17, 0
	s_cbranch_scc1 .LBB0_828
	v_add_u32_e32 v0, s31, v6
	v_mad_i64_i32 v[0:1], s[42:43], v0, s97, v[4:5]
	global_load_dwordx4 v[198:201], v[0:1], off
	s_mov_b64 s[42:43], 0

.LBB0_370:
	s_add_i32 s42, s18, s38
	v_ashrrev_i32_e32 v19, 31, v18
	s_waitcnt vmcnt(0)
	v_mad_i64_i32 v[0:1], s[42:43], s42, 3, v[18:19]
	v_readlane_b32 s42, v255, 7
	v_readlane_b32 s43, v255, 8
	s_movk_i32 s44, 0xc00
	s_nop 0
	v_mov_b64_e32 v[2:3], s[42:43]
	v_mad_u64_u32 v[2:3], s[42:43], v0, s44, v[2:3]
	v_mad_i32_i24 v3, v1, s44, v3
	v_lshlrev_b32_e32 v0, 2, v171
	v_mov_b32_e32 v1, v64
	v_lshl_add_u64 v[6:7], v[2:3], 0, v[0:1]
	global_load_dwordx4 v[198:201], v[6:7], off offset:2048
	s_nop 0
	global_load_dwordx4 v[6:9], v[6:7], off offset:2064
	s_waitcnt vmcnt(1)
	v_cvt_pk_bf16_f32 v198, v198, v199
	v_cvt_pk_bf16_f32 v199, v200, v201
	s_waitcnt vmcnt(0)
	v_cvt_pk_bf16_f32 v200, v6, v7
	v_cvt_pk_bf16_f32 v201, v8, v9
.LBB0_371:
.LBB0_372:
	s_andn2_saveexec_b64 s[12:13], s[12:13]
	s_cbranch_execz .LBB0_376
	v_cmp_gt_u32_e32 vcc, s28, v6
	v_mov_b32_e32 v201, 0
	v_mov_b32_e32 v200, 0
	v_mov_b32_e32 v199, 0
	v_mov_b32_e32 v198, 0
	s_and_saveexec_b64 s[42:43], vcc
	s_cbranch_execz .LBB0_375
	v_add_u32_e32 v0, s31, v6
	v_mad_i64_i32 v[0:1], s[44:45], v0, s97, v[4:5]
	global_load_dwordx4 v[198:201], v[0:1], off

.LBB0_376:
	s_or_b64 exec, exec, s[12:13]
	v_lshl_add_u32 v219, v18, 7, v170
	s_or_b64 exec, exec, s[40:41]
	s_and_saveexec_b64 s[40:41], s[48:49]
	s_cbranch_execnz .LBB0_325

.LBB0_378:
	v_add_u32_e32 v6, -3, v22
	v_cmp_gt_i32_e32 vcc, 3, v22
	s_and_saveexec_b64 s[12:13], vcc
	s_xor_b64 s[12:13], exec, s[12:13]
	s_cbranch_execz .LBB0_385
	s_andn2_b64 vcc, exec, s[20:21]
	s_mov_b64 s[42:43], -1
	s_cbranch_vccnz .LBB0_382
	s_cmp_eq_u32 s17, 0
	s_cbranch_scc1 .LBB0_829
	v_add_u32_e32 v0, s31, v6
	v_mad_i64_i32 v[0:1], s[42:43], v0, s97, v[4:5]
	global_load_dwordx4 v[202:205], v[0:1], off
	s_mov_b64 s[42:43], 0

.LBB0_383:
	s_add_i32 s42, s18, s38
	v_ashrrev_i32_e32 v23, 31, v22
	s_waitcnt vmcnt(0)
	v_mad_i64_i32 v[0:1], s[42:43], s42, 3, v[22:23]
	v_readlane_b32 s42, v255, 7
	v_readlane_b32 s43, v255, 8
	s_movk_i32 s44, 0xc00
	s_nop 0
	v_mov_b64_e32 v[2:3], s[42:43]
	v_mad_u64_u32 v[2:3], s[42:43], v0, s44, v[2:3]
	v_mad_i32_i24 v3, v1, s44, v3
	v_lshlrev_b32_e32 v0, 2, v171
	v_mov_b32_e32 v1, v64
	v_lshl_add_u64 v[6:7], v[2:3], 0, v[0:1]
	global_load_dwordx4 v[202:205], v[6:7], off offset:2048
	s_nop 0
	global_load_dwordx4 v[6:9], v[6:7], off offset:2064
	s_waitcnt vmcnt(1)
	v_cvt_pk_bf16_f32 v202, v202, v203
	v_cvt_pk_bf16_f32 v203, v204, v205
	s_waitcnt vmcnt(0)
	v_cvt_pk_bf16_f32 v204, v6, v7
	v_cvt_pk_bf16_f32 v205, v8, v9
.LBB0_384:
.LBB0_385:
	s_andn2_saveexec_b64 s[12:13], s[12:13]
	s_cbranch_execz .LBB0_389
	v_cmp_gt_u32_e32 vcc, s28, v6
	v_mov_b32_e32 v205, 0
	v_mov_b32_e32 v204, 0
	v_mov_b32_e32 v203, 0
	v_mov_b32_e32 v202, 0
	s_and_saveexec_b64 s[42:43], vcc
	s_cbranch_execz .LBB0_388
	v_add_u32_e32 v0, s31, v6
	v_mad_i64_i32 v[0:1], s[44:45], v0, s97, v[4:5]
	global_load_dwordx4 v[202:205], v[0:1], off

.LBB0_389:
	s_or_b64 exec, exec, s[12:13]
	v_lshl_add_u32 v228, v22, 7, v170
	s_or_b64 exec, exec, s[40:41]
	s_and_saveexec_b64 s[40:41], s[52:53]
	s_cbranch_execnz .LBB0_338

.LBB0_391:
	v_add_u32_e32 v6, -3, v26
	v_cmp_gt_i32_e32 vcc, 3, v26
	s_and_saveexec_b64 s[12:13], vcc
	s_xor_b64 s[12:13], exec, s[12:13]
	s_cbranch_execz .LBB0_398
	s_andn2_b64 vcc, exec, s[20:21]
	s_mov_b64 s[42:43], -1
	s_cbranch_vccnz .LBB0_395
	s_cmp_eq_u32 s17, 0
	s_cbranch_scc1 .LBB0_830
	v_add_u32_e32 v0, s31, v6
	v_mad_i64_i32 v[0:1], s[42:43], v0, s97, v[4:5]
	global_load_dwordx4 v[206:209], v[0:1], off
	s_mov_b64 s[42:43], 0

.LBB0_396:
	s_add_i32 s42, s18, s38
	v_ashrrev_i32_e32 v27, 31, v26
	s_waitcnt vmcnt(0)
	v_mad_i64_i32 v[0:1], s[42:43], s42, 3, v[26:27]
	v_readlane_b32 s42, v255, 7
	v_readlane_b32 s43, v255, 8
	s_movk_i32 s44, 0xc00
	s_nop 0
	v_mov_b64_e32 v[2:3], s[42:43]
	v_mad_u64_u32 v[2:3], s[42:43], v0, s44, v[2:3]
	v_mad_i32_i24 v3, v1, s44, v3
	v_lshlrev_b32_e32 v0, 2, v171
	v_mov_b32_e32 v1, v64
	v_lshl_add_u64 v[6:7], v[2:3], 0, v[0:1]
	global_load_dwordx4 v[206:209], v[6:7], off offset:2048
	s_nop 0
	global_load_dwordx4 v[6:9], v[6:7], off offset:2064
	s_waitcnt vmcnt(1)
	v_cvt_pk_bf16_f32 v206, v206, v207
	v_cvt_pk_bf16_f32 v207, v208, v209
	s_waitcnt vmcnt(0)
	v_cvt_pk_bf16_f32 v208, v6, v7
	v_cvt_pk_bf16_f32 v209, v8, v9
.LBB0_397:
.LBB0_398:
	s_andn2_saveexec_b64 s[12:13], s[12:13]
	s_cbranch_execz .LBB0_402
	v_cmp_gt_u32_e32 vcc, s28, v6
	v_mov_b32_e32 v209, 0
	v_mov_b32_e32 v208, 0
	v_mov_b32_e32 v207, 0
	v_mov_b32_e32 v206, 0
	s_and_saveexec_b64 s[42:43], vcc
	s_cbranch_execz .LBB0_401
	v_add_u32_e32 v0, s31, v6
	v_mad_i64_i32 v[0:1], s[44:45], v0, s97, v[4:5]
	global_load_dwordx4 v[206:209], v[0:1], off

.LBB0_402:
	s_or_b64 exec, exec, s[12:13]
	v_lshl_add_u32 v229, v26, 7, v170
	s_or_b64 exec, exec, s[40:41]
	s_and_saveexec_b64 s[40:41], s[56:57]
	s_cbranch_execz .LBB0_415

.LBB0_415:
	s_or_b64 exec, exec, s[40:41]
	s_waitcnt vmcnt(0)
	ds_write_b128 v214, v[178:181] offset:18432
	ds_write_b128 v215, v[182:185] offset:18432
	ds_write_b128 v216, v[186:189] offset:18432
	ds_write_b128 v217, v[190:193] offset:18432
	ds_write_b128 v218, v[194:197] offset:18432
	ds_write_b128 v219, v[198:201] offset:18432
	ds_write_b128 v228, v[202:205] offset:18432
	ds_write_b128 v229, v[206:209] offset:18432
	s_waitcnt vmcnt(0) lgkmcnt(0)
	s_mov_b64 s[40:41], -1
	s_and_b64 vcc, exec, s[20:21]
	s_cbranch_vccz .LBB0_418
	s_mov_b64 s[40:41], 0
	s_cmp_lg_u32 s17, 63
	s_mov_b64 s[12:13], 0
	s_cbranch_scc1 .LBB0_418
	s_lshl_b32 s12, s29, 3
	s_add_i32 s6, s6, s12
	s_mul_hi_i32 s13, s6, 0x2400
	s_mulk_i32 s6, 0x2400
	s_add_u32 s12, s77, s6
	s_addc_u32 s13, s79, s13

.LBB0_814:
	v_mov_b32_e32 v181, 0
	v_mov_b32_e32 v180, v181
	v_mov_b32_e32 v179, v181
	v_mov_b32_e32 v178, v181
	s_cbranch_execz .LBB0_176
	s_branch .LBB0_177
.LBB0_815:
	v_mov_b32_e32 v185, 0
	v_mov_b32_e32 v184, v185
	v_mov_b32_e32 v183, v185
	v_mov_b32_e32 v182, v185
	s_cbranch_execz .LBB0_189
	s_branch .LBB0_190
.LBB0_816:
	v_mov_b32_e32 v189, 0
	v_mov_b32_e32 v188, v189
	v_mov_b32_e32 v187, v189
	v_mov_b32_e32 v186, v189
	s_cbranch_execz .LBB0_202
	s_branch .LBB0_203
.LBB0_817:
	v_mov_b32_e32 v193, 0
	v_mov_b32_e32 v192, v193
	v_mov_b32_e32 v191, v193
	v_mov_b32_e32 v190, v193
	s_cbranch_execz .LBB0_215
	s_branch .LBB0_216
.LBB0_818:
	v_mov_b32_e32 v197, 0
	v_mov_b32_e32 v196, v197
	v_mov_b32_e32 v195, v197
	v_mov_b32_e32 v194, v197
	s_cbranch_execz .LBB0_228
	s_branch .LBB0_229
.LBB0_819:
	v_mov_b32_e32 v201, 0
	v_mov_b32_e32 v200, v201
	v_mov_b32_e32 v199, v201
	v_mov_b32_e32 v198, v201
	s_cbranch_execz .LBB0_241
	s_branch .LBB0_242
.LBB0_820:
	v_mov_b32_e32 v205, 0
	v_mov_b32_e32 v204, v205
	v_mov_b32_e32 v203, v205
	v_mov_b32_e32 v202, v205
	s_cbranch_execz .LBB0_254
	s_branch .LBB0_255
.LBB0_821:
	v_mov_b32_e32 v209, 0
	v_mov_b32_e32 v208, v209
	v_mov_b32_e32 v207, v209
	v_mov_b32_e32 v206, v209
	s_cbranch_execz .LBB0_267
	s_branch .LBB0_268
